# norm phases: next plain row's four loads issued into free VGPRs before the current row is reduced/scaled/stored (software prefetch), on top of the late stagger barrier
# speedup vs baseline: 1.0003x; 1.0003x over previous
.LBB0_1168:
	v_readfirstlane_b32 s2, v204
	s_lshr_b32 s2, s2, 6
	s_lshl_b32 s3, s80, 3
	s_add_i32 s4, s2, s3
	s_cmpk_gt_i32 s4, 0x41ff
	s_cbranch_scc1 .LBB0_1175
	s_load_dword s6, s[78:79], 0x118
	s_waitcnt vmcnt(0)
	v_and_b32_e32 v4, 63, v204
	v_mov_b32_e32 v1, 0
	v_lshlrev_b32_e32 v0, 4, v4
	v_lshl_add_u64 v[2:3], s[90:91], 0, v[0:1]
	s_waitcnt lgkmcnt(0)
	s_lshl_b32 s6, s6, 3
	s_mov_b64 s[8:9], 0x1d000000
	s_ashr_i32 s7, s3, 31
	v_lshl_add_u64 v[22:23], v[2:3], 0, s[8:9]
	v_lshlrev_b32_e32 v2, 3, v4
	v_mov_b32_e32 v3, v1
	s_add_u32 s2, s2, s3
	v_lshl_add_u64 v[2:3], s[90:91], 0, v[2:3]
	s_mov_b64 s[8:9], 0x5800000
	s_addc_u32 s3, 0, s7
	s_ashr_i32 s7, s6, 31
	v_lshl_add_u64 v[24:25], v[2:3], 0, s[8:9]
	s_lshl_b64 s[8:9], s[2:3], 10
	s_lshl_b64 s[10:11], s[6:7], 10
	s_lshl_b64 s[2:3], s[2:3], 12
	s_add_u32 s2, s88, s2
	s_addc_u32 s3, s89, s3
	v_lshl_add_u64 v[20:21], s[88:89], 0, v[0:1]
	v_lshl_add_u64 v[26:27], s[2:3], 0, v[0:1]
	v_mbcnt_lo_u32_b32 v0, -1, 0
	v_mbcnt_hi_u32_b32 v30, -1, v0
	v_and_b32_e32 v0, 64, v30
	s_mov_b32 s5, 0
	s_lshl_b64 s[12:13], s[6:7], 12
	s_mov_b32 s7, 0x200000
	s_mov_b32 s16, 0x400000
	s_mov_b32 s17, 0x600000
	s_mov_b32 s18, 0x800000
	s_mov_b32 s19, 0xa00000
	s_mov_b32 s20, 0xc00000
	s_mov_b32 s21, 0xe00000
	v_mov_b32_e32 v28, 0x358637bd
	s_mov_b32 s22, 0xf800000
	v_mov_b32_e32 v29, 0x260
	s_movk_i32 s23, 0x7fff
	v_add_u32_e32 v31, 64, v0
	v_xor_b32_e32 v32, 1, v30
	v_xor_b32_e32 v33, 2, v30
	v_xor_b32_e32 v34, 4, v30
	v_xor_b32_e32 v35, 8, v30
	v_xor_b32_e32 v36, 16, v30
	v_xor_b32_e32 v37, 32, v30
	v_mov_b32_e32 v38, 1
	s_mov_b32 s31, 0
	s_branch .LBB0_1171

.LBB0_1173:
	s_andn2_b64 vcc, exec, s[2:3]
	s_cbranch_vccnz .LBB0_1170
	s_cmp_eq_u32 s31, 1
	s_cbranch_scc1 .Lnp_have_1
	global_load_dwordx4 v[12:15], v[26:27], off
	global_load_dwordx4 v[8:11], v[26:27], off offset:1024
	global_load_dwordx4 v[0:3], v[26:27], off offset:3072
	global_load_dwordx4 v[4:7], v[26:27], off offset:2048
	v_cmp_lt_i32_e32 vcc, v32, v31
	s_mov_b64 s[14:15], s[8:9]
	s_waitcnt vmcnt(3)
	v_pk_mul_f32 v[18:19], v[12:13], v[12:13]
	v_cndmask_b32_e32 v16, v30, v32, vcc
	v_lshlrev_b32_e32 v39, 2, v16
	v_pk_mul_f32 v[16:17], v[14:15], v[14:15]
	s_waitcnt vmcnt(2) lgkmcnt(0)
	v_pk_mul_f32 v[40:41], v[10:11], v[10:11]
	v_pk_mul_f32 v[42:43], v[8:9], v[8:9]
	v_pk_mov_b32 v[48:49], v[18:19], v[16:17] op_sel:[1,0]
	v_mov_b32_e32 v19, v17
	v_pk_mov_b32 v[16:17], v[42:43], v[40:41] op_sel:[1,0]
	v_mov_b32_e32 v43, v41
	s_waitcnt vmcnt(1)
	v_mul_f32_e32 v47, v0, v0
	s_waitcnt vmcnt(0)
	s_add_i32 s30, s4, s6
	s_cmpk_lt_i32 s30, 0x4000
	s_cselect_b32 s31, 1, 0
	s_cbranch_scc0 .Lnp_skipa_1
	v_lshl_add_u64 v[236:237], v[26:27], 0, s[12:13]
	global_load_dwordx4 v[220:223], v[236:237], off
	global_load_dwordx4 v[224:227], v[236:237], off offset:1024
	global_load_dwordx4 v[228:231], v[236:237], off offset:3072
	global_load_dwordx4 v[232:235], v[236:237], off offset:2048
.Lnp_skipa_1:
	v_mul_f32_e32 v44, v5, v5
	v_mul_f32_e32 v46, v7, v7
	v_pk_add_f32 v[18:19], v[48:49], v[18:19]
	v_pk_add_f32 v[16:17], v[16:17], v[42:43]
	v_mul_f32_e32 v50, v1, v1
	v_mul_f32_e32 v51, v2, v2
	v_mul_f32_e32 v52, v3, v3
	v_pk_fma_f32 v[40:41], v[4:5], v[4:5], v[44:45] op_sel_hi:[1,1,0]
	v_pk_fma_f32 v[44:45], v[6:7], v[6:7], v[46:47] op_sel_hi:[1,1,0]
	v_pk_add_f32 v[18:19], v[18:19], v[18:19] op_sel:[0,1] op_sel_hi:[1,0]
	v_pk_add_f32 v[16:17], v[16:17], v[16:17] op_sel:[0,1] op_sel_hi:[1,0]
	v_mov_b32_e32 v41, v51
	v_mov_b32_e32 v45, v52
	v_mov_b32_e32 v19, v47
	v_mov_b32_e32 v17, v50
	v_pk_add_f32 v[40:41], v[40:41], v[44:45]
	v_pk_add_f32 v[16:17], v[18:19], v[16:17]
	v_cmp_lt_i32_e32 vcc, v33, v31
	v_pk_add_f32 v[16:17], v[16:17], v[40:41]
	s_nop 0
	v_add_f32_e32 v16, v16, v17
	ds_bpermute_b32 v17, v39, v16
	v_cndmask_b32_e32 v18, v30, v33, vcc
	v_lshlrev_b32_e32 v18, 2, v18
	v_cmp_lt_i32_e32 vcc, v34, v31
	s_waitcnt lgkmcnt(0)
	v_add_f32_e32 v16, v16, v17
	ds_bpermute_b32 v17, v18, v16
	v_cndmask_b32_e32 v19, v30, v34, vcc
	v_lshlrev_b32_e32 v19, 2, v19
	v_cmp_lt_i32_e32 vcc, v35, v31
	s_waitcnt lgkmcnt(0)
	v_add_f32_e32 v16, v16, v17
	ds_bpermute_b32 v17, v19, v16
	v_cndmask_b32_e32 v18, v30, v35, vcc
	v_lshlrev_b32_e32 v18, 2, v18
	v_cmp_lt_i32_e32 vcc, v36, v31
	s_waitcnt lgkmcnt(0)
	v_add_f32_e32 v16, v16, v17
	ds_bpermute_b32 v17, v18, v16
	v_cndmask_b32_e32 v39, v30, v36, vcc
	v_lshlrev_b32_e32 v39, 2, v39
	v_cmp_lt_i32_e32 vcc, v37, v31
	v_mov_b32_e32 v18, v13
	s_waitcnt lgkmcnt(0)
	v_add_f32_e32 v16, v16, v17
	ds_bpermute_b32 v17, v39, v16
	v_cndmask_b32_e32 v19, v30, v37, vcc
	v_lshlrev_b32_e32 v40, 2, v19
	v_mov_b32_e32 v19, v15
	v_mov_b32_e32 v13, v14
	s_waitcnt lgkmcnt(0)
	v_add_f32_e32 v39, v16, v17
	ds_bpermute_b32 v40, v40, v39
	v_mov_b32_e32 v14, v9
	v_mov_b32_e32 v15, v11
	v_mov_b32_e32 v9, v10
	v_mov_b32_e32 v10, v5
	v_mov_b32_e32 v11, v7
	v_mov_b32_e32 v5, v6
	v_mov_b32_e32 v6, v1
	v_mov_b32_e32 v7, v3
	v_mov_b32_e32 v1, v2
	s_branch .LBB0_1170
.Lnp_have_1:
	s_waitcnt vmcnt(4)
	v_mov_b64_e32 v[12:13], v[220:221]
	v_mov_b64_e32 v[14:15], v[222:223]
	v_mov_b64_e32 v[8:9], v[224:225]
	v_mov_b64_e32 v[10:11], v[226:227]
	v_mov_b64_e32 v[0:1], v[228:229]
	v_mov_b64_e32 v[2:3], v[230:231]
	v_mov_b64_e32 v[4:5], v[232:233]
	v_mov_b64_e32 v[6:7], v[234:235]
	s_add_i32 s30, s4, s6
	s_cmpk_lt_i32 s30, 0x4000
	s_cselect_b32 s31, 1, 0
	s_cbranch_scc0 .Lnp_skipb_1
	v_lshl_add_u64 v[236:237], v[26:27], 0, s[12:13]
	global_load_dwordx4 v[220:223], v[236:237], off
	global_load_dwordx4 v[224:227], v[236:237], off offset:1024
	global_load_dwordx4 v[228:231], v[236:237], off offset:3072
	global_load_dwordx4 v[232:235], v[236:237], off offset:2048
.Lnp_skipb_1:
	v_cmp_lt_i32_e32 vcc, v32, v31
	s_mov_b64 s[14:15], s[8:9]
	v_pk_mul_f32 v[18:19], v[12:13], v[12:13]
	v_cndmask_b32_e32 v16, v30, v32, vcc
	v_lshlrev_b32_e32 v39, 2, v16
	v_pk_mul_f32 v[16:17], v[14:15], v[14:15]
	s_waitcnt lgkmcnt(0)
	v_pk_mul_f32 v[40:41], v[10:11], v[10:11]
	v_pk_mul_f32 v[42:43], v[8:9], v[8:9]
	v_pk_mov_b32 v[48:49], v[18:19], v[16:17] op_sel:[1,0]
	v_mov_b32_e32 v19, v17
	v_pk_mov_b32 v[16:17], v[42:43], v[40:41] op_sel:[1,0]
	v_mov_b32_e32 v43, v41
	v_mul_f32_e32 v47, v0, v0
	v_mul_f32_e32 v44, v5, v5
	v_mul_f32_e32 v46, v7, v7
	v_pk_add_f32 v[18:19], v[48:49], v[18:19]
	v_pk_add_f32 v[16:17], v[16:17], v[42:43]
	v_mul_f32_e32 v50, v1, v1
	v_mul_f32_e32 v51, v2, v2
	v_mul_f32_e32 v52, v3, v3
	v_pk_fma_f32 v[40:41], v[4:5], v[4:5], v[44:45] op_sel_hi:[1,1,0]
	v_pk_fma_f32 v[44:45], v[6:7], v[6:7], v[46:47] op_sel_hi:[1,1,0]
	v_pk_add_f32 v[18:19], v[18:19], v[18:19] op_sel:[0,1] op_sel_hi:[1,0]
	v_pk_add_f32 v[16:17], v[16:17], v[16:17] op_sel:[0,1] op_sel_hi:[1,0]
	v_mov_b32_e32 v41, v51
	v_mov_b32_e32 v45, v52
	v_mov_b32_e32 v19, v47
	v_mov_b32_e32 v17, v50
	v_pk_add_f32 v[40:41], v[40:41], v[44:45]
	v_pk_add_f32 v[16:17], v[18:19], v[16:17]
	v_cmp_lt_i32_e32 vcc, v33, v31
	v_pk_add_f32 v[16:17], v[16:17], v[40:41]
	s_nop 0
	v_add_f32_e32 v16, v16, v17
	ds_bpermute_b32 v17, v39, v16
	v_cndmask_b32_e32 v18, v30, v33, vcc
	v_lshlrev_b32_e32 v18, 2, v18
	v_cmp_lt_i32_e32 vcc, v34, v31
	s_waitcnt lgkmcnt(0)
	v_add_f32_e32 v16, v16, v17
	ds_bpermute_b32 v17, v18, v16
	v_cndmask_b32_e32 v19, v30, v34, vcc
	v_lshlrev_b32_e32 v19, 2, v19
	v_cmp_lt_i32_e32 vcc, v35, v31
	s_waitcnt lgkmcnt(0)
	v_add_f32_e32 v16, v16, v17
	ds_bpermute_b32 v17, v19, v16
	v_cndmask_b32_e32 v18, v30, v35, vcc
	v_lshlrev_b32_e32 v18, 2, v18
	v_cmp_lt_i32_e32 vcc, v36, v31
	s_waitcnt lgkmcnt(0)
	v_add_f32_e32 v16, v16, v17
	ds_bpermute_b32 v17, v18, v16
	v_cndmask_b32_e32 v39, v30, v36, vcc
	v_lshlrev_b32_e32 v39, 2, v39
	v_cmp_lt_i32_e32 vcc, v37, v31
	v_mov_b32_e32 v18, v13
	s_waitcnt lgkmcnt(0)
	v_add_f32_e32 v16, v16, v17
	ds_bpermute_b32 v17, v39, v16
	v_cndmask_b32_e32 v19, v30, v37, vcc
	v_lshlrev_b32_e32 v40, 2, v19
	v_mov_b32_e32 v19, v15
	v_mov_b32_e32 v13, v14
	s_waitcnt lgkmcnt(0)
	v_add_f32_e32 v39, v16, v17
	ds_bpermute_b32 v40, v40, v39
	v_mov_b32_e32 v14, v9
	v_mov_b32_e32 v15, v11
	v_mov_b32_e32 v9, v10
	v_mov_b32_e32 v10, v5
	v_mov_b32_e32 v11, v7
	v_mov_b32_e32 v5, v6
	v_mov_b32_e32 v6, v1
	v_mov_b32_e32 v7, v3
	v_mov_b32_e32 v1, v2
	s_branch .LBB0_1170

.LBB0_1410:
	v_readfirstlane_b32 s0, v204
	s_lshr_b32 s2, s0, 6
	s_lshl_b32 s3, s80, 3
	s_add_i32 s0, s2, s3
	s_cmpk_gt_i32 s0, 0x41ff
	s_cbranch_scc1 .LBB0_1417
	s_load_dword s6, s[78:79], 0x118
	s_waitcnt vmcnt(0)
	v_and_b32_e32 v4, 63, v204
	v_mov_b32_e32 v1, 0
	v_lshlrev_b32_e32 v0, 4, v4
	v_lshl_add_u64 v[2:3], s[90:91], 0, v[0:1]
	s_waitcnt lgkmcnt(0)
	s_lshl_b32 s6, s6, 3
	s_mov_b64 s[8:9], 0x1d000000
	s_ashr_i32 s7, s3, 31
	v_lshl_add_u64 v[22:23], v[2:3], 0, s[8:9]
	v_lshlrev_b32_e32 v2, 3, v4
	v_mov_b32_e32 v3, v1
	s_add_u32 s2, s2, s3
	v_lshl_add_u64 v[2:3], s[90:91], 0, v[2:3]
	s_mov_b64 s[8:9], 0x5800000
	s_addc_u32 s3, 0, s7
	s_ashr_i32 s7, s6, 31
	v_lshl_add_u64 v[24:25], v[2:3], 0, s[8:9]
	s_lshl_b64 s[8:9], s[2:3], 10
	s_lshl_b64 s[10:11], s[6:7], 10
	s_lshl_b64 s[2:3], s[2:3], 12
	s_add_u32 s2, s88, s2
	s_addc_u32 s3, s89, s3
	v_lshl_add_u64 v[20:21], s[88:89], 0, v[0:1]
	v_lshl_add_u64 v[26:27], s[2:3], 0, v[0:1]
	v_mbcnt_lo_u32_b32 v0, -1, 0
	v_mbcnt_hi_u32_b32 v32, -1, v0
	v_and_b32_e32 v0, 64, v32
	s_mov_b32 s1, 0
	s_lshl_b64 s[12:13], s[6:7], 12
	s_mov_b32 s7, 0x200000
	s_mov_b32 s16, 0x400000
	s_mov_b32 s17, 0x600000
	s_mov_b32 s18, 0x800000
	s_mov_b32 s19, 0xa00000
	s_mov_b32 s20, 0xc00000
	s_mov_b32 s21, 0xe00000
	s_mov_b32 s22, 0x1000000
	s_mov_b32 s23, 0x1200000
	s_mov_b32 s24, 0x1400000
	v_mov_b32_e32 v30, 0x358637bd
	s_mov_b32 s25, 0xf800000
	v_mov_b32_e32 v31, 0x260
	s_movk_i32 s26, 0x7fff
	v_add_u32_e32 v33, 64, v0
	v_xor_b32_e32 v34, 1, v32
	v_xor_b32_e32 v35, 2, v32
	v_xor_b32_e32 v36, 4, v32
	v_xor_b32_e32 v37, 8, v32
	v_xor_b32_e32 v38, 16, v32
	v_xor_b32_e32 v39, 32, v32
	v_mov_b32_e32 v40, 1
	s_mov_b32 s31, 0
	s_branch .LBB0_1413

.LBB0_1415:
	s_andn2_b64 vcc, exec, s[2:3]
	s_cbranch_vccnz .LBB0_1412
	s_cmp_eq_u32 s31, 1
	s_cbranch_scc1 .Lnp_have_2
	global_load_dwordx4 v[12:15], v[26:27], off
	global_load_dwordx4 v[8:11], v[26:27], off offset:1024
	global_load_dwordx4 v[0:3], v[26:27], off offset:3072
	global_load_dwordx4 v[4:7], v[26:27], off offset:2048
	v_cmp_lt_i32_e32 vcc, v34, v33
	s_mov_b64 s[14:15], s[8:9]
	s_waitcnt vmcnt(3)
	v_pk_mul_f32 v[18:19], v[12:13], v[12:13]
	v_cndmask_b32_e32 v16, v32, v34, vcc
	v_lshlrev_b32_e32 v41, 2, v16
	v_pk_mul_f32 v[16:17], v[14:15], v[14:15]
	s_waitcnt vmcnt(2) lgkmcnt(0)
	v_pk_mul_f32 v[28:29], v[10:11], v[10:11]
	v_pk_mul_f32 v[42:43], v[8:9], v[8:9]
	v_pk_mov_b32 v[48:49], v[18:19], v[16:17] op_sel:[1,0]
	v_mov_b32_e32 v19, v17
	v_pk_mov_b32 v[16:17], v[42:43], v[28:29] op_sel:[1,0]
	v_mov_b32_e32 v43, v29
	s_waitcnt vmcnt(1)
	v_mul_f32_e32 v47, v0, v0
	s_waitcnt vmcnt(0)
	s_add_i32 s30, s0, s6
	s_cmpk_lt_i32 s30, 0x4000
	s_cselect_b32 s31, 1, 0
	s_cbranch_scc0 .Lnp_skipa_2
	v_lshl_add_u64 v[236:237], v[26:27], 0, s[12:13]
	global_load_dwordx4 v[220:223], v[236:237], off
	global_load_dwordx4 v[224:227], v[236:237], off offset:1024
	global_load_dwordx4 v[228:231], v[236:237], off offset:3072
	global_load_dwordx4 v[232:235], v[236:237], off offset:2048
.Lnp_skipa_2:
	v_mul_f32_e32 v44, v5, v5
	v_mul_f32_e32 v46, v7, v7
	v_pk_add_f32 v[18:19], v[48:49], v[18:19]
	v_pk_add_f32 v[16:17], v[16:17], v[42:43]
	v_mul_f32_e32 v50, v1, v1
	v_mul_f32_e32 v51, v2, v2
	v_mul_f32_e32 v52, v3, v3
	v_pk_fma_f32 v[28:29], v[4:5], v[4:5], v[44:45] op_sel_hi:[1,1,0]
	v_pk_fma_f32 v[44:45], v[6:7], v[6:7], v[46:47] op_sel_hi:[1,1,0]
	v_pk_add_f32 v[18:19], v[18:19], v[18:19] op_sel:[0,1] op_sel_hi:[1,0]
	v_pk_add_f32 v[16:17], v[16:17], v[16:17] op_sel:[0,1] op_sel_hi:[1,0]
	v_mov_b32_e32 v29, v51
	v_mov_b32_e32 v45, v52
	v_mov_b32_e32 v19, v47
	v_mov_b32_e32 v17, v50
	v_pk_add_f32 v[28:29], v[28:29], v[44:45]
	v_pk_add_f32 v[16:17], v[18:19], v[16:17]
	v_cmp_lt_i32_e32 vcc, v35, v33
	v_pk_add_f32 v[16:17], v[16:17], v[28:29]
	s_nop 0
	v_add_f32_e32 v16, v16, v17
	ds_bpermute_b32 v17, v41, v16
	v_cndmask_b32_e32 v18, v32, v35, vcc
	v_lshlrev_b32_e32 v18, 2, v18
	v_cmp_lt_i32_e32 vcc, v36, v33
	s_waitcnt lgkmcnt(0)
	v_add_f32_e32 v16, v16, v17
	ds_bpermute_b32 v17, v18, v16
	v_cndmask_b32_e32 v19, v32, v36, vcc
	v_lshlrev_b32_e32 v19, 2, v19
	v_cmp_lt_i32_e32 vcc, v37, v33
	s_waitcnt lgkmcnt(0)
	v_add_f32_e32 v16, v16, v17
	ds_bpermute_b32 v17, v19, v16
	v_cndmask_b32_e32 v18, v32, v37, vcc
	v_lshlrev_b32_e32 v18, 2, v18
	v_cmp_lt_i32_e32 vcc, v38, v33
	s_waitcnt lgkmcnt(0)
	v_add_f32_e32 v16, v16, v17
	ds_bpermute_b32 v17, v18, v16
	v_cndmask_b32_e32 v28, v32, v38, vcc
	v_lshlrev_b32_e32 v28, 2, v28
	v_cmp_lt_i32_e32 vcc, v39, v33
	v_mov_b32_e32 v18, v13
	s_waitcnt lgkmcnt(0)
	v_add_f32_e32 v16, v16, v17
	ds_bpermute_b32 v17, v28, v16
	v_cndmask_b32_e32 v19, v32, v39, vcc
	v_lshlrev_b32_e32 v29, 2, v19
	v_mov_b32_e32 v19, v15
	v_mov_b32_e32 v13, v14
	s_waitcnt lgkmcnt(0)
	v_add_f32_e32 v28, v16, v17
	ds_bpermute_b32 v29, v29, v28
	v_mov_b32_e32 v14, v9
	v_mov_b32_e32 v15, v11
	v_mov_b32_e32 v9, v10
	v_mov_b32_e32 v10, v5
	v_mov_b32_e32 v11, v7
	v_mov_b32_e32 v5, v6
	v_mov_b32_e32 v6, v1
	v_mov_b32_e32 v7, v3
	v_mov_b32_e32 v1, v2
	s_branch .LBB0_1412
.Lnp_have_2:
	s_waitcnt vmcnt(4)
	v_mov_b64_e32 v[12:13], v[220:221]
	v_mov_b64_e32 v[14:15], v[222:223]
	v_mov_b64_e32 v[8:9], v[224:225]
	v_mov_b64_e32 v[10:11], v[226:227]
	v_mov_b64_e32 v[0:1], v[228:229]
	v_mov_b64_e32 v[2:3], v[230:231]
	v_mov_b64_e32 v[4:5], v[232:233]
	v_mov_b64_e32 v[6:7], v[234:235]
	s_add_i32 s30, s0, s6
	s_cmpk_lt_i32 s30, 0x4000
	s_cselect_b32 s31, 1, 0
	s_cbranch_scc0 .Lnp_skipb_2
	v_lshl_add_u64 v[236:237], v[26:27], 0, s[12:13]
	global_load_dwordx4 v[220:223], v[236:237], off
	global_load_dwordx4 v[224:227], v[236:237], off offset:1024
	global_load_dwordx4 v[228:231], v[236:237], off offset:3072
	global_load_dwordx4 v[232:235], v[236:237], off offset:2048
.Lnp_skipb_2:
	v_cmp_lt_i32_e32 vcc, v34, v33
	s_mov_b64 s[14:15], s[8:9]
	v_pk_mul_f32 v[18:19], v[12:13], v[12:13]
	v_cndmask_b32_e32 v16, v32, v34, vcc
	v_lshlrev_b32_e32 v41, 2, v16
	v_pk_mul_f32 v[16:17], v[14:15], v[14:15]
	s_waitcnt lgkmcnt(0)
	v_pk_mul_f32 v[28:29], v[10:11], v[10:11]
	v_pk_mul_f32 v[42:43], v[8:9], v[8:9]
	v_pk_mov_b32 v[48:49], v[18:19], v[16:17] op_sel:[1,0]
	v_mov_b32_e32 v19, v17
	v_pk_mov_b32 v[16:17], v[42:43], v[28:29] op_sel:[1,0]
	v_mov_b32_e32 v43, v29
	v_mul_f32_e32 v47, v0, v0
	v_mul_f32_e32 v44, v5, v5
	v_mul_f32_e32 v46, v7, v7
	v_pk_add_f32 v[18:19], v[48:49], v[18:19]
	v_pk_add_f32 v[16:17], v[16:17], v[42:43]
	v_mul_f32_e32 v50, v1, v1
	v_mul_f32_e32 v51, v2, v2
	v_mul_f32_e32 v52, v3, v3
	v_pk_fma_f32 v[28:29], v[4:5], v[4:5], v[44:45] op_sel_hi:[1,1,0]
	v_pk_fma_f32 v[44:45], v[6:7], v[6:7], v[46:47] op_sel_hi:[1,1,0]
	v_pk_add_f32 v[18:19], v[18:19], v[18:19] op_sel:[0,1] op_sel_hi:[1,0]
	v_pk_add_f32 v[16:17], v[16:17], v[16:17] op_sel:[0,1] op_sel_hi:[1,0]
	v_mov_b32_e32 v29, v51
	v_mov_b32_e32 v45, v52
	v_mov_b32_e32 v19, v47
	v_mov_b32_e32 v17, v50
	v_pk_add_f32 v[28:29], v[28:29], v[44:45]
	v_pk_add_f32 v[16:17], v[18:19], v[16:17]
	v_cmp_lt_i32_e32 vcc, v35, v33
	v_pk_add_f32 v[16:17], v[16:17], v[28:29]
	s_nop 0
	v_add_f32_e32 v16, v16, v17
	ds_bpermute_b32 v17, v41, v16
	v_cndmask_b32_e32 v18, v32, v35, vcc
	v_lshlrev_b32_e32 v18, 2, v18
	v_cmp_lt_i32_e32 vcc, v36, v33
	s_waitcnt lgkmcnt(0)
	v_add_f32_e32 v16, v16, v17
	ds_bpermute_b32 v17, v18, v16
	v_cndmask_b32_e32 v19, v32, v36, vcc
	v_lshlrev_b32_e32 v19, 2, v19
	v_cmp_lt_i32_e32 vcc, v37, v33
	s_waitcnt lgkmcnt(0)
	v_add_f32_e32 v16, v16, v17
	ds_bpermute_b32 v17, v19, v16
	v_cndmask_b32_e32 v18, v32, v37, vcc
	v_lshlrev_b32_e32 v18, 2, v18
	v_cmp_lt_i32_e32 vcc, v38, v33
	s_waitcnt lgkmcnt(0)
	v_add_f32_e32 v16, v16, v17
	ds_bpermute_b32 v17, v18, v16
	v_cndmask_b32_e32 v28, v32, v38, vcc
	v_lshlrev_b32_e32 v28, 2, v28
	v_cmp_lt_i32_e32 vcc, v39, v33
	v_mov_b32_e32 v18, v13
	s_waitcnt lgkmcnt(0)
	v_add_f32_e32 v16, v16, v17
	ds_bpermute_b32 v17, v28, v16
	v_cndmask_b32_e32 v19, v32, v39, vcc
	v_lshlrev_b32_e32 v29, 2, v19
	v_mov_b32_e32 v19, v15
	v_mov_b32_e32 v13, v14
	s_waitcnt lgkmcnt(0)
	v_add_f32_e32 v28, v16, v17
	ds_bpermute_b32 v29, v29, v28
	v_mov_b32_e32 v14, v9
	v_mov_b32_e32 v15, v11
	v_mov_b32_e32 v9, v10
	v_mov_b32_e32 v10, v5
	v_mov_b32_e32 v11, v7
	v_mov_b32_e32 v5, v6
	v_mov_b32_e32 v6, v1
	v_mov_b32_e32 v7, v3
	v_mov_b32_e32 v1, v2
	s_branch .LBB0_1412

.Lbar_ret_19:
.LBB0_2320:
	v_readfirstlane_b32 s2, v204
	s_lshr_b32 s2, s2, 6
	s_lshl_b32 s3, s80, 3
	s_add_i32 s4, s2, s3
	s_cmpk_gt_i32 s4, 0x41ff
	s_cbranch_scc1 .LBB0_2327
	s_load_dword s6, s[78:79], 0x118
	s_waitcnt vmcnt(0)
	v_and_b32_e32 v4, 63, v204
	v_mov_b32_e32 v1, 0
	v_lshlrev_b32_e32 v0, 4, v4
	v_lshl_add_u64 v[2:3], s[90:91], 0, v[0:1]
	s_waitcnt lgkmcnt(0)
	s_lshl_b32 s6, s6, 3
	s_mov_b64 s[8:9], 0x1d000000
	s_ashr_i32 s7, s3, 31
	v_lshl_add_u64 v[22:23], v[2:3], 0, s[8:9]
	v_lshlrev_b32_e32 v2, 3, v4
	v_mov_b32_e32 v3, v1
	s_add_u32 s2, s2, s3
	v_lshl_add_u64 v[2:3], s[90:91], 0, v[2:3]
	s_mov_b64 s[8:9], 0x5800000
	s_addc_u32 s3, 0, s7
	s_ashr_i32 s7, s6, 31
	v_lshl_add_u64 v[24:25], v[2:3], 0, s[8:9]
	s_lshl_b64 s[8:9], s[2:3], 10
	s_lshl_b64 s[10:11], s[6:7], 10
	s_lshl_b64 s[2:3], s[2:3], 12
	s_add_u32 s2, s88, s2
	s_addc_u32 s3, s89, s3
	v_lshl_add_u64 v[20:21], s[88:89], 0, v[0:1]
	v_lshl_add_u64 v[26:27], s[2:3], 0, v[0:1]
	v_mbcnt_lo_u32_b32 v0, -1, 0
	v_mbcnt_hi_u32_b32 v30, -1, v0
	v_and_b32_e32 v0, 64, v30
	s_mov_b32 s5, 0
	s_lshl_b64 s[12:13], s[6:7], 12
	s_mov_b32 s7, 0x200000
	s_mov_b32 s16, 0x400000
	s_mov_b32 s17, 0x600000
	s_mov_b32 s18, 0x800000
	s_mov_b32 s19, 0xa00000
	s_mov_b32 s20, 0xc00000
	s_mov_b32 s21, 0xe00000
	v_mov_b32_e32 v28, 0x358637bd
	s_mov_b32 s22, 0xf800000
	v_mov_b32_e32 v29, 0x260
	s_movk_i32 s23, 0x7fff
	v_add_u32_e32 v31, 64, v0
	v_xor_b32_e32 v32, 1, v30
	v_xor_b32_e32 v33, 2, v30
	v_xor_b32_e32 v34, 4, v30
	v_xor_b32_e32 v35, 8, v30
	v_xor_b32_e32 v36, 16, v30
	v_xor_b32_e32 v37, 32, v30
	v_mov_b32_e32 v38, 1
	s_mov_b32 s31, 0
	s_branch .LBB0_2323
